# v28 plus attnprep 16-lane xor shuffles via DPP instead of LDS bpermute
# baseline (speedup 1.0000x reference)
.LBB0_370:
	s_or_b64 exec, exec, s[8:9]
	v_add_u32_e32 v48, 0xfffff000, v54
	v_lshrrev_b32_e32 v48, 12, v48
	v_ashrrev_i32_e32 v74, 8, v54
	v_add_u32_e32 v48, 16, v48
	v_cndmask_b32_e64 v48, v48, v74, s[14:15]
	v_mul_i32_i24_e32 v100, 48, v48
	s_waitcnt vmcnt(0)
	v_lshlrev_b32_e32 v48, 16, v44
	v_and_b32_e32 v49, 0xffff0000, v44
	v_lshlrev_b32_e32 v50, 16, v45
	v_and_b32_e32 v51, 0xffff0000, v45
	v_pk_mul_f32 v[44:45], v[48:49], v[48:49]
	v_lshlrev_b32_e32 v76, 16, v46
	v_and_b32_e32 v77, 0xffff0000, v46
	v_lshlrev_b32_e32 v94, 16, v47
	v_and_b32_e32 v95, 0xffff0000, v47
	v_pk_mul_f32 v[46:47], v[50:51], v[50:51]
	v_add_f32_e32 v44, v44, v45
	v_add_f32_e32 v44, v44, v46
	v_pk_mul_f32 v[96:97], v[76:77], v[76:77]
	v_add_f32_e32 v44, v47, v44
	v_add_f32_e32 v44, v96, v44
	v_pk_mul_f32 v[98:99], v[94:95], v[94:95]
	v_add_f32_e32 v44, v97, v44
	v_add_f32_e32 v44, v98, v44
	v_add_f32_e32 v44, v99, v44
	s_nop 1
	v_mov_b32_dpp v45, v44 quad_perm:[1,0,3,2] row_mask:0xf bank_mask:0xf
	s_waitcnt lgkmcnt(0)
	v_add_f32_e32 v44, v44, v45
	s_nop 1
	v_mov_b32_dpp v45, v44 quad_perm:[2,3,0,1] row_mask:0xf bank_mask:0xf
	s_waitcnt lgkmcnt(0)
	v_add_f32_e32 v44, v44, v45
	s_nop 1
	v_mov_b32_dpp v45, v44 row_shl:4 row_mask:0xf bank_mask:0x5
	v_mov_b32_dpp v45, v44 row_shr:4 row_mask:0xf bank_mask:0xa
	s_waitcnt lgkmcnt(0)
	v_add_f32_e32 v44, v44, v45
	s_nop 1
	v_mov_b32_dpp v45, v44 row_shl:8 row_mask:0xf bank_mask:0x3
	v_mov_b32_dpp v45, v44 row_shr:8 row_mask:0xf bank_mask:0xc
	s_waitcnt lgkmcnt(0)
	v_add_f32_e32 v44, v44, v45
	v_fmamk_f32 v44, v44, 0x3c000000, v206
	v_cmp_gt_f32_e32 vcc, s96, v44
	v_mul_f32_e32 v45, 0x4b800000, v44
	s_nop 0
	v_cndmask_b32_e32 v44, v44, v45, vcc
	v_rsq_f32_e32 v44, v44
	s_nop 0
	v_mul_f32_e32 v45, 0x45800000, v44
	v_cndmask_b32_e32 v92, v44, v45, vcc
	v_pk_mul_f32 v[44:45], v[0:1], v[92:93] op_sel_hi:[1,0]
	v_pk_mul_f32 v[46:47], v[2:3], v[92:93] op_sel_hi:[1,0]
	v_pk_mul_f32 v[44:45], v[44:45], v[48:49]
	v_pk_mul_f32 v[48:49], v[4:5], v[92:93] op_sel_hi:[1,0]
	v_pk_mul_f32 v[46:47], v[46:47], v[50:51]
	v_pk_mul_f32 v[48:49], v[48:49], v[76:77]
	v_pk_mul_f32 v[50:51], v[6:7], v[92:93] op_sel_hi:[1,0]
	v_pk_mul_f32 v[76:77], v[44:45], v[44:45]
	v_pk_mul_f32 v[50:51], v[50:51], v[94:95]
	v_pk_mul_f32 v[94:95], v[46:47], v[46:47]
	v_add_f32_e32 v75, v76, v77
	v_add_f32_e32 v75, v94, v75
	v_pk_mul_f32 v[96:97], v[48:49], v[48:49]
	v_add_f32_e32 v75, v95, v75
	v_add_f32_e32 v75, v96, v75
	v_pk_mul_f32 v[98:99], v[50:51], v[50:51]
	v_add_f32_e32 v75, v97, v75
	v_add_f32_e32 v75, v98, v75
	v_add_f32_e32 v75, v99, v75
	s_nop 1
	v_mov_b32_dpp v76, v75 quad_perm:[1,0,3,2] row_mask:0xf bank_mask:0xf
	v_add_u32_e32 v92, v53, v100
	s_waitcnt lgkmcnt(0)
	v_add_f32_e32 v75, v75, v76
	s_nop 1
	v_mov_b32_dpp v76, v75 quad_perm:[2,3,0,1] row_mask:0xf bank_mask:0xf
	s_waitcnt lgkmcnt(0)
	v_add_f32_e32 v75, v75, v76
	s_nop 1
	v_mov_b32_dpp v76, v75 row_shl:4 row_mask:0xf bank_mask:0x5
	v_mov_b32_dpp v76, v75 row_shr:4 row_mask:0xf bank_mask:0xa
	s_waitcnt lgkmcnt(0)
	v_add_f32_e32 v75, v75, v76
	s_nop 1
	v_mov_b32_dpp v76, v75 row_shl:8 row_mask:0xf bank_mask:0x3
	v_mov_b32_dpp v76, v75 row_shr:8 row_mask:0xf bank_mask:0xc
	s_and_saveexec_b64 s[8:9], s[12:13]
	s_cbranch_execz .LBB0_372
	s_waitcnt lgkmcnt(0)
	v_add_f32_e32 v75, v75, v76
	s_mov_b32 s18, 0xf800000
	v_mul_f32_e32 v76, 0x4f800000, v75
	v_cmp_gt_f32_e32 vcc, s18, v75
	s_nop 1
	v_cndmask_b32_e32 v75, v75, v76, vcc
	v_sqrt_f32_e32 v76, v75
	s_nop 0
	v_add_u32_e32 v77, -1, v76
	v_fma_f32 v95, -v77, v76, v75
	v_add_u32_e32 v94, 1, v76
	v_cmp_ge_f32_e64 s[18:19], 0, v95
	s_nop 1
	v_cndmask_b32_e64 v77, v76, v77, s[18:19]
	v_fma_f32 v76, -v94, v76, v75
	v_cmp_lt_f32_e64 s[18:19], 0, v76
	s_nop 1
	v_cndmask_b32_e64 v76, v77, v94, s[18:19]
	v_mul_f32_e32 v77, 0x37800000, v76
	v_cndmask_b32_e32 v76, v76, v77, vcc
	v_cmp_class_f32_e32 vcc, v75, v214
	s_nop 1
	v_cndmask_b32_e32 v75, v76, v75, vcc
	ds_max_u32 v92, v75
.LBB0_372:
	s_or_b64 exec, exec, s[8:9]
	s_and_saveexec_b64 s[8:9], s[16:17]
	s_xor_b64 s[8:9], exec, s[8:9]
	s_cbranch_execz .LBB0_374
	s_waitcnt lgkmcnt(0)
	s_nop 4
	v_mov_b32_dpp v76, v44 row_shl:4 row_mask:0xf bank_mask:0x5
	v_mov_b32_dpp v76, v44 row_shr:4 row_mask:0xf bank_mask:0xa
	s_nop 4
	v_mov_b32_dpp v77, v45 row_shl:4 row_mask:0xf bank_mask:0x5
	v_mov_b32_dpp v77, v45 row_shr:4 row_mask:0xf bank_mask:0xa
	s_waitcnt lgkmcnt(0)
	v_pk_mul_f32 v[76:77], v[28:29], v[76:77]
	s_nop 0
	v_cndmask_b32_e64 v77, v77, -v77, s[6:7]
	v_cndmask_b32_e64 v76, v76, -v76, s[6:7]
	v_pk_fma_f32 v[44:45], v[24:25], v[44:45], v[76:77]
	s_nop 1
	v_mov_b32_dpp v76, v46 row_shl:4 row_mask:0xf bank_mask:0x5
	v_mov_b32_dpp v76, v46 row_shr:4 row_mask:0xf bank_mask:0xa
	s_nop 1
	v_mov_b32_dpp v77, v47 row_shl:4 row_mask:0xf bank_mask:0x5
	v_mov_b32_dpp v77, v47 row_shr:4 row_mask:0xf bank_mask:0xa
	s_waitcnt lgkmcnt(0)
	v_pk_mul_f32 v[76:77], v[30:31], v[76:77]
	s_nop 0
	v_cndmask_b32_e64 v77, v77, -v77, s[6:7]
	v_cndmask_b32_e64 v76, v76, -v76, s[6:7]
	v_pk_fma_f32 v[46:47], v[26:27], v[46:47], v[76:77]
	s_nop 1
	v_mov_b32_dpp v76, v48 row_shl:4 row_mask:0xf bank_mask:0x5
	v_mov_b32_dpp v76, v48 row_shr:4 row_mask:0xf bank_mask:0xa
	s_nop 1
	v_mov_b32_dpp v77, v49 row_shl:4 row_mask:0xf bank_mask:0x5
	v_mov_b32_dpp v77, v49 row_shr:4 row_mask:0xf bank_mask:0xa
	s_waitcnt lgkmcnt(0)
	v_pk_mul_f32 v[76:77], v[16:17], v[76:77]
	s_nop 0
	v_cndmask_b32_e64 v77, v77, -v77, s[6:7]
	v_cndmask_b32_e64 v76, v76, -v76, s[6:7]
	v_pk_fma_f32 v[48:49], v[20:21], v[48:49], v[76:77]
	s_nop 1
	v_mov_b32_dpp v76, v50 row_shl:4 row_mask:0xf bank_mask:0x5
	v_mov_b32_dpp v76, v50 row_shr:4 row_mask:0xf bank_mask:0xa
	s_nop 1
	v_mov_b32_dpp v77, v51 row_shl:4 row_mask:0xf bank_mask:0x5
	v_mov_b32_dpp v77, v51 row_shr:4 row_mask:0xf bank_mask:0xa
	s_waitcnt lgkmcnt(0)
	v_pk_mul_f32 v[76:77], v[18:19], v[76:77]
	s_nop 0
	v_cndmask_b32_e64 v77, v77, -v77, s[6:7]
	v_cndmask_b32_e64 v76, v76, -v76, s[6:7]
	v_pk_fma_f32 v[50:51], v[22:23], v[50:51], v[76:77]

.LBB0_378:
	s_or_b64 exec, exec, s[8:9]
	s_nop 0
	v_lshlrev_b32_e32 v44, 16, v40
	v_and_b32_e32 v45, 0xffff0000, v40
	v_lshlrev_b32_e32 v46, 16, v41
	v_and_b32_e32 v47, 0xffff0000, v41
	v_pk_mul_f32 v[40:41], v[44:45], v[44:45]
	v_lshlrev_b32_e32 v38, 16, v43
	v_lshlrev_b32_e32 v36, 16, v42
	v_and_b32_e32 v39, 0xffff0000, v43
	v_and_b32_e32 v37, 0xffff0000, v42
	v_pk_mul_f32 v[42:43], v[46:47], v[46:47]
	v_add_f32_e32 v40, v40, v41
	v_add_f32_e32 v40, v40, v42
	v_pk_mul_f32 v[48:49], v[36:37], v[36:37]
	v_add_f32_e32 v40, v43, v40
	v_add_f32_e32 v40, v48, v40
	v_pk_mul_f32 v[50:51], v[38:39], v[38:39]
	v_add_f32_e32 v40, v49, v40
	v_add_f32_e32 v40, v50, v40
	v_add_f32_e32 v40, v51, v40
	s_nop 1
	v_mov_b32_dpp v41, v40 quad_perm:[1,0,3,2] row_mask:0xf bank_mask:0xf
	s_waitcnt lgkmcnt(0)
	v_add_f32_e32 v40, v40, v41
	s_nop 1
	v_mov_b32_dpp v41, v40 quad_perm:[2,3,0,1] row_mask:0xf bank_mask:0xf
	s_waitcnt lgkmcnt(0)
	v_add_f32_e32 v40, v40, v41
	s_nop 1
	v_mov_b32_dpp v41, v40 row_shl:4 row_mask:0xf bank_mask:0x5
	v_mov_b32_dpp v41, v40 row_shr:4 row_mask:0xf bank_mask:0xa
	s_waitcnt lgkmcnt(0)
	v_add_f32_e32 v40, v40, v41
	s_nop 1
	v_mov_b32_dpp v41, v40 row_shl:8 row_mask:0xf bank_mask:0x3
	v_mov_b32_dpp v41, v40 row_shr:8 row_mask:0xf bank_mask:0xc
	s_and_saveexec_b64 s[8:9], s[12:13]
	s_cbranch_execz .LBB0_380
	s_waitcnt lgkmcnt(0)
	v_add_f32_e32 v40, v40, v41
	s_mov_b32 s18, 0xf800000
	v_mul_f32_e32 v41, 0x4f800000, v40
	v_cmp_gt_f32_e32 vcc, s18, v40
	s_nop 1
	v_cndmask_b32_e32 v40, v40, v41, vcc
	v_sqrt_f32_e32 v41, v40
	s_nop 0
	v_add_u32_e32 v42, -1, v41
	v_fma_f32 v48, -v42, v41, v40
	v_add_u32_e32 v43, 1, v41
	v_cmp_ge_f32_e64 s[18:19], 0, v48
	s_nop 1
	v_cndmask_b32_e64 v42, v41, v42, s[18:19]
	v_fma_f32 v41, -v43, v41, v40
	v_cmp_lt_f32_e64 s[18:19], 0, v41
	s_nop 1
	v_cndmask_b32_e64 v41, v42, v43, s[18:19]
	v_mul_f32_e32 v42, 0x37800000, v41
	v_cndmask_b32_e32 v41, v41, v42, vcc
	v_cmp_class_f32_e32 vcc, v40, v214
	s_nop 1
	v_cndmask_b32_e32 v40, v41, v40, vcc
	ds_max_u32 v92, v40 offset:16
.LBB0_380:
	s_or_b64 exec, exec, s[8:9]
	s_and_saveexec_b64 s[8:9], s[16:17]
	s_xor_b64 s[8:9], exec, s[8:9]
	s_cbranch_execz .LBB0_382
	s_nop 4
	v_mov_b32_dpp v40, v44 row_shl:4 row_mask:0xf bank_mask:0x5
	v_mov_b32_dpp v40, v44 row_shr:4 row_mask:0xf bank_mask:0xa
	s_waitcnt lgkmcnt(1)
	s_nop 4
	v_mov_b32_dpp v41, v45 row_shl:4 row_mask:0xf bank_mask:0x5
	v_mov_b32_dpp v41, v45 row_shr:4 row_mask:0xf bank_mask:0xa
	s_nop 1
	v_mov_b32_dpp v42, v46 row_shl:4 row_mask:0xf bank_mask:0x5
	v_mov_b32_dpp v42, v46 row_shr:4 row_mask:0xf bank_mask:0xa
	s_nop 1
	v_mov_b32_dpp v43, v47 row_shl:4 row_mask:0xf bank_mask:0x5
	v_mov_b32_dpp v43, v47 row_shr:4 row_mask:0xf bank_mask:0xa
	s_waitcnt lgkmcnt(2)
	v_pk_mul_f32 v[40:41], v[28:29], v[40:41]
	s_nop 0
	v_cndmask_b32_e64 v41, v41, -v41, s[6:7]
	v_cndmask_b32_e64 v40, v40, -v40, s[6:7]
	v_pk_fma_f32 v[40:41], v[24:25], v[44:45], v[40:41]
	s_nop 1
	v_mov_b32_dpp v44, v36 row_shl:4 row_mask:0xf bank_mask:0x5
	v_mov_b32_dpp v44, v36 row_shr:4 row_mask:0xf bank_mask:0xa
	s_nop 1
	v_mov_b32_dpp v45, v37 row_shl:4 row_mask:0xf bank_mask:0x5
	v_mov_b32_dpp v45, v37 row_shr:4 row_mask:0xf bank_mask:0xa
	s_waitcnt lgkmcnt(2)
	v_pk_mul_f32 v[42:43], v[30:31], v[42:43]
	s_waitcnt lgkmcnt(0)
	v_pk_mul_f32 v[44:45], v[16:17], v[44:45]
	s_nop 0
	v_cndmask_b32_e64 v45, v45, -v45, s[6:7]
	v_cndmask_b32_e64 v44, v44, -v44, s[6:7]
	v_pk_fma_f32 v[44:45], v[20:21], v[36:37], v[44:45]
	s_nop 1
	v_mov_b32_dpp v36, v38 row_shl:4 row_mask:0xf bank_mask:0x5
	v_mov_b32_dpp v36, v38 row_shr:4 row_mask:0xf bank_mask:0xa
	s_nop 1
	v_mov_b32_dpp v37, v39 row_shl:4 row_mask:0xf bank_mask:0x5
	v_mov_b32_dpp v37, v39 row_shr:4 row_mask:0xf bank_mask:0xa
	v_cndmask_b32_e64 v43, v43, -v43, s[6:7]
	v_cndmask_b32_e64 v42, v42, -v42, s[6:7]
	v_pk_fma_f32 v[42:43], v[26:27], v[46:47], v[42:43]
	s_waitcnt lgkmcnt(0)
	v_pk_mul_f32 v[36:37], v[18:19], v[36:37]
	s_nop 0
	v_cndmask_b32_e64 v37, v37, -v37, s[6:7]
	v_cndmask_b32_e64 v36, v36, -v36, s[6:7]
	v_pk_fma_f32 v[46:47], v[22:23], v[38:39], v[36:37]
	v_cvt_pk_bf16_f32 v36, v40, v41
	v_cvt_pk_bf16_f32 v37, v42, v43
	v_cvt_pk_bf16_f32 v38, v44, v45
	v_cvt_pk_bf16_f32 v39, v46, v47
	global_store_dwordx4 v[70:71], v[36:39], off offset:2048

.LBB0_384:
	s_or_b64 exec, exec, s[8:9]
	v_lshlrev_b32_e32 v40, 16, v32
	v_and_b32_e32 v41, 0xffff0000, v32
	v_lshlrev_b32_e32 v42, 16, v33
	v_and_b32_e32 v43, 0xffff0000, v33
	v_pk_mul_f32 v[32:33], v[40:41], v[40:41]
	v_lshlrev_b32_e32 v38, 16, v35
	v_lshlrev_b32_e32 v36, 16, v34
	v_and_b32_e32 v39, 0xffff0000, v35
	v_and_b32_e32 v37, 0xffff0000, v34
	v_pk_mul_f32 v[34:35], v[42:43], v[42:43]
	v_add_f32_e32 v32, v32, v33
	v_add_f32_e32 v32, v32, v34
	v_pk_mul_f32 v[44:45], v[36:37], v[36:37]
	v_add_f32_e32 v32, v35, v32
	v_add_f32_e32 v32, v44, v32
	v_pk_mul_f32 v[46:47], v[38:39], v[38:39]
	v_add_f32_e32 v32, v45, v32
	v_add_f32_e32 v32, v46, v32
	v_add_f32_e32 v32, v47, v32
	s_nop 1
	v_mov_b32_dpp v33, v32 quad_perm:[1,0,3,2] row_mask:0xf bank_mask:0xf
	s_waitcnt lgkmcnt(0)
	v_add_f32_e32 v32, v32, v33
	s_nop 1
	v_mov_b32_dpp v33, v32 quad_perm:[2,3,0,1] row_mask:0xf bank_mask:0xf
	s_waitcnt lgkmcnt(0)
	v_add_f32_e32 v32, v32, v33
	s_nop 1
	v_mov_b32_dpp v33, v32 row_shl:4 row_mask:0xf bank_mask:0x5
	v_mov_b32_dpp v33, v32 row_shr:4 row_mask:0xf bank_mask:0xa
	s_waitcnt lgkmcnt(0)
	v_add_f32_e32 v32, v32, v33
	s_nop 1
	v_mov_b32_dpp v33, v32 row_shl:8 row_mask:0xf bank_mask:0x3
	v_mov_b32_dpp v33, v32 row_shr:8 row_mask:0xf bank_mask:0xc
	s_and_saveexec_b64 s[8:9], s[12:13]
	s_cbranch_execz .LBB0_388
	s_waitcnt lgkmcnt(0)
	v_add_f32_e32 v32, v32, v33
	s_mov_b32 s18, 0xf800000
	v_mul_f32_e32 v33, 0x4f800000, v32
	v_cmp_gt_f32_e32 vcc, s18, v32
	s_nop 1
	v_cndmask_b32_e32 v32, v32, v33, vcc
	v_sqrt_f32_e32 v33, v32
	s_nop 0
	v_add_u32_e32 v34, -1, v33
	v_fma_f32 v44, -v34, v33, v32
	v_add_u32_e32 v35, 1, v33
	v_cmp_ge_f32_e64 s[18:19], 0, v44
	s_nop 1
	v_cndmask_b32_e64 v34, v33, v34, s[18:19]
	v_fma_f32 v33, -v35, v33, v32
	v_cmp_lt_f32_e64 s[18:19], 0, v33
	s_nop 1
	v_cndmask_b32_e64 v33, v34, v35, s[18:19]
	v_mul_f32_e32 v34, 0x37800000, v33
	v_cndmask_b32_e32 v33, v33, v34, vcc
	v_cmp_class_f32_e32 vcc, v32, v214
	s_nop 1
	v_cndmask_b32_e32 v32, v33, v32, vcc
	ds_max_u32 v92, v32 offset:32
	s_or_b64 exec, exec, s[8:9]
	s_and_saveexec_b64 s[8:9], s[16:17]
	s_xor_b64 s[8:9], exec, s[8:9]
	s_cbranch_execnz .LBB0_389

.LBB0_389:
	s_nop 4
	v_mov_b32_dpp v32, v40 row_shl:4 row_mask:0xf bank_mask:0x5
	v_mov_b32_dpp v32, v40 row_shr:4 row_mask:0xf bank_mask:0xa
	s_waitcnt lgkmcnt(1)
	s_nop 4
	v_mov_b32_dpp v33, v41 row_shl:4 row_mask:0xf bank_mask:0x5
	v_mov_b32_dpp v33, v41 row_shr:4 row_mask:0xf bank_mask:0xa
	s_waitcnt lgkmcnt(0)
	v_pk_mul_f32 v[28:29], v[28:29], v[32:33]
	s_nop 0
	v_cndmask_b32_e64 v29, v29, -v29, s[6:7]
	v_cndmask_b32_e64 v28, v28, -v28, s[6:7]
	v_pk_fma_f32 v[24:25], v[24:25], v[40:41], v[28:29]
	s_nop 1
	v_mov_b32_dpp v28, v42 row_shl:4 row_mask:0xf bank_mask:0x5
	v_mov_b32_dpp v28, v42 row_shr:4 row_mask:0xf bank_mask:0xa
	s_nop 1
	v_mov_b32_dpp v29, v43 row_shl:4 row_mask:0xf bank_mask:0x5
	v_mov_b32_dpp v29, v43 row_shr:4 row_mask:0xf bank_mask:0xa
	s_waitcnt lgkmcnt(0)
	v_pk_mul_f32 v[28:29], v[30:31], v[28:29]
	s_nop 0
	v_cndmask_b32_e64 v29, v29, -v29, s[6:7]
	v_cndmask_b32_e64 v28, v28, -v28, s[6:7]
	v_pk_fma_f32 v[26:27], v[26:27], v[42:43], v[28:29]
	s_nop 1
	v_mov_b32_dpp v28, v36 row_shl:4 row_mask:0xf bank_mask:0x5
	v_mov_b32_dpp v28, v36 row_shr:4 row_mask:0xf bank_mask:0xa
	s_nop 1
	v_mov_b32_dpp v29, v37 row_shl:4 row_mask:0xf bank_mask:0x5
	v_mov_b32_dpp v29, v37 row_shr:4 row_mask:0xf bank_mask:0xa
	s_waitcnt lgkmcnt(0)
	v_pk_mul_f32 v[16:17], v[16:17], v[28:29]
	s_nop 0
	v_cndmask_b32_e64 v17, v17, -v17, s[6:7]
	v_cndmask_b32_e64 v16, v16, -v16, s[6:7]
	v_pk_fma_f32 v[20:21], v[20:21], v[36:37], v[16:17]
	s_nop 1
	v_mov_b32_dpp v16, v38 row_shl:4 row_mask:0xf bank_mask:0x5
	v_mov_b32_dpp v16, v38 row_shr:4 row_mask:0xf bank_mask:0xa
	s_nop 1
	v_mov_b32_dpp v17, v39 row_shl:4 row_mask:0xf bank_mask:0x5
	v_mov_b32_dpp v17, v39 row_shr:4 row_mask:0xf bank_mask:0xa
	s_waitcnt lgkmcnt(0)
	v_pk_mul_f32 v[16:17], v[18:19], v[16:17]
	s_nop 0
	v_cndmask_b32_e64 v17, v17, -v17, s[6:7]
	v_cndmask_b32_e64 v16, v16, -v16, s[6:7]
	v_pk_fma_f32 v[22:23], v[22:23], v[38:39], v[16:17]
	v_cvt_pk_bf16_f32 v16, v24, v25
	v_cvt_pk_bf16_f32 v17, v26, v27
	v_cvt_pk_bf16_f32 v18, v20, v21
	v_cvt_pk_bf16_f32 v19, v22, v23
	global_store_dwordx4 v[70:71], v[16:19], off offset:3072
	s_andn2_saveexec_b64 s[8:9], s[8:9]
	s_cbranch_execnz .LBB0_387
